# one static s_setprio 1 for waves 4-7 over the P1 GEMM units (reset at the side task), on top of the v27 stack
# speedup vs baseline: 1.0021x; 1.0021x over previous
; #define PG8_STAGE(bufoff, gbase, voff) do { _Pragma("unroll") for (int _i = 0; _i < 2; ++_i) \
;         __builtin_amdgcn_global_load_lds((const unsigned*)((const char*)(gbase) + (voff)[_i]), (LAS unsigned*)(lds + (bufoff) + ldsw + _i * 8192), 16, 0, 0); } while (0)
; #define PG8_LDA(dst, b, h) do { _Pragma("unroll") for (int m = 0; m < 4; ++m) _Pragma("unroll") for (int k = 0; k < 2; ++k) dst[m][k] = *(const LAS bf16x8*)(lds + PG8_SA(b, h) + aoff + m * 2048 + k * 1024); } while (0)
; #define PG8_LDB(dst, b, h) do { _Pragma("unroll") for (int n = 0; n < 2; ++n) _Pragma("unroll") for (int k = 0; k < 2; ++k) dst[n][k] = *(const LAS bf16x8*)(lds + PG8_SB(b, h) + boff + n * 2048 + k * 1024); } while (0)
; #define PG8_MMA(ai, bj, At, Bt) do { __builtin_amdgcn_s_setprio(1); _Pragma("unroll") for (int m = 0; m < 4; ++m) _Pragma("unroll") for (int n = 0; n < 2; ++n) _Pragma("unroll") for (int k = 0; k < 2; ++k) \
;         acc[ai][bj][m][n] = __builtin_amdgcn_mfma_f32_16x16x32_bf16(Bt[n][k], At[m][k], acc[ai][bj][m][n], 0, 0, 0); __builtin_amdgcn_s_setprio(0); } while (0)
; #define PG8_WAIT_V(n) asm volatile("s_waitcnt vmcnt(" #n ")" ::: "memory")
; #define PG8_WAIT_L(n) asm volatile("s_waitcnt lgkmcnt(" #n ")" ::: "memory")
; #define PG8_BAR __builtin_amdgcn_s_barrier()
; #define PG8_SCHED __builtin_amdgcn_sched_barrier(0)
; template <class Epi, class Sched, int NSEG, bool ALIGN_EPI = true, bool AFTER_DRAIN = false>
; __device__ __forceinline__ void gemm_phase(LAS unsigned char* lds, const Gemm g, const Sched& S, const Epi& E) {
;     ...
;         const bool has_next = S.next(ui + 1, nxt);
;         const char* nA = has_next ? PG8_ABASE(nxt) : cA; const char* nB = has_next ? PG8_BBASE(nxt) : cB;
;         for (int t = 0; t < nt; t += 2) {
;             const bool last = (t == nt - 2);
;             const char* a1 = cA + (size_t)(t + 1) * kstep;
;             const char* a2 = last ? nA : cA + (size_t)(t + 2) * kstep; const char* b2 = last ? nB : cB + (size_t)(t + 2) * kstep;
;             const char* a3 = a2 + kstep; const char* b3 = b2 + kstep;
;             PG8_LDB(B0, 0, 0); PG8_LDB(B1, 0, 1); PG8_SCHED; PG8_LDA(At, 0, 0); PG8_STAGE(PG8_SA(1, 1), a1 + hstep, voffA);
;             PG8_WAIT_V(8); PG8_WAIT_L(0); PG8_BAR; PG8_MMA(0, 0, At, B0); PG8_MMA(0, 1, At, B1); PG8_BAR; PG8_SCHED;
.LBB0_326:
	ds_read_b128 v[192:195], v164 offset:0
	ds_read_b128 v[196:199], v164 offset:1024
	ds_read_b128 v[200:203], v164 offset:2048
	ds_read_b128 v[204:207], v164 offset:3072
	ds_read_b128 v[208:211], v164 offset:4096
	ds_read_b128 v[212:215], v164 offset:5120
	ds_read_b128 v[216:219], v164 offset:6144
	ds_read_b128 v[220:223], v164 offset:7168
	ds_read_b128 v[128:131], v162 offset:0
	ds_read_b128 v[132:135], v162 offset:1024
	ds_read_b128 v[166:169], v162 offset:2048
	ds_read_b128 v[170:173], v162 offset:3072
	s_ashr_i32 s19, s18, 31
	s_lshl_b64 s[20:21], s[18:19], 20
	s_add_u32 s20, s4, s20
	s_addc_u32 s21, s5, s21
	v_readlane_b32 s52, v248, 29
	s_and_b64 s[22:23], s[0:1], exec
	v_readlane_b32 s53, v248, 30
	v_readlane_b32 s54, v248, 31
	v_readlane_b32 s55, v248, 32
	v_readlane_b32 s56, v248, 33
	v_readlane_b32 s57, v248, 34
	s_cselect_b32 s3, s21, s27
	s_cselect_b32 s19, s20, s26
	s_ashr_i32 s17, s16, 31
	v_readlane_b32 s58, v248, 35
	v_readlane_b32 s59, v248, 36
	s_mov_b64 s[52:53], s[56:57]
	s_lshl_b64 s[22:23], s[16:17], 20
	s_mov_b64 s[54:55], s[58:59]
	s_add_u32 s22, s54, s22
	s_addc_u32 s23, s55, s23
	s_and_b64 s[30:31], s[0:1], exec
	s_cselect_b32 s17, s23, s29
	s_cselect_b32 s25, s22, s28
	s_waitcnt lgkmcnt(0)
	s_barrier
	v_readfirstlane_b32 s81, v186
	s_nop 3
	s_lshr_b32 s81, s81, 8
	s_cmp_lg_u32 s81, 0
	s_cbranch_scc0 .Lp1prio_skip
	s_setprio 1
.Lp1prio_skip:
	s_add_u32 s74, s72, 0x80000
	s_addc_u32 s75, s73, 0
	s_add_u32 s78, s76, 0x80000
	s_addc_u32 s79, s77, 0
	v_mfma_f32_16x16x32_bf16 v[124:127], v[128:131], v[192:195], 0
	ds_read_b128 v[174:177], v162 offset:16384
	v_mfma_f32_16x16x32_bf16 v[120:123], v[166:169], v[192:195], 0
	ds_read_b128 v[178:181], v162 offset:17408
	v_mfma_f32_16x16x32_bf16 v[108:111], v[128:131], v[200:203], 0
	ds_read_b128 v[182:185], v162 offset:18432
	v_mfma_f32_16x16x32_bf16 v[104:107], v[166:169], v[200:203], 0
	ds_read_b128 v[188:191], v162 offset:19456
	v_mfma_f32_16x16x32_bf16 v[92:95], v[128:131], v[208:211], 0
	s_mov_b32 m0, s33
	v_mfma_f32_16x16x32_bf16 v[88:91], v[166:169], v[208:211], 0
	global_load_lds_dwordx4 v138, s[72:73]
	v_mfma_f32_16x16x32_bf16 v[76:79], v[128:131], v[216:219], 0
	ds_read_b128 v[224:227], v164 offset:16384
	v_mfma_f32_16x16x32_bf16 v[72:75], v[166:169], v[216:219], 0
	ds_read_b128 v[228:231], v164 offset:17408
	v_mfma_f32_16x16x32_bf16 v[124:127], v[132:135], v[196:199], v[124:127]
	ds_read_b128 v[232:235], v164 offset:18432
	v_mfma_f32_16x16x32_bf16 v[120:123], v[170:173], v[196:199], v[120:123]
	ds_read_b128 v[236:239], v164 offset:19456
	v_mfma_f32_16x16x32_bf16 v[108:111], v[132:135], v[204:207], v[108:111]
	s_add_i32 m0, s33, 0x2000
	v_mfma_f32_16x16x32_bf16 v[104:107], v[170:173], v[204:207], v[104:107]
	global_load_lds_dwordx4 v142, s[72:73]
	v_mfma_f32_16x16x32_bf16 v[92:95], v[132:135], v[212:215], v[92:95]
	ds_read_b128 v[240:243], v164 offset:20480
	v_mfma_f32_16x16x32_bf16 v[88:91], v[170:173], v[212:215], v[88:91]
	ds_read_b128 v[244:247], v164 offset:21504
	v_mfma_f32_16x16x32_bf16 v[76:79], v[132:135], v[220:223], v[76:79]
	ds_read_b128 v[250:253], v164 offset:22528
	v_mfma_f32_16x16x32_bf16 v[72:75], v[170:173], v[220:223], v[72:75]
	ds_read_b128 v[150:153], v164 offset:23552
	s_waitcnt lgkmcnt(8)
	v_mfma_f32_16x16x32_bf16 v[116:119], v[174:177], v[192:195], 0
	s_add_i32 m0, s33, 0x10000
	v_mfma_f32_16x16x32_bf16 v[112:115], v[182:185], v[192:195], 0
	global_load_lds_dwordx4 v140, s[76:77]
	v_mfma_f32_16x16x32_bf16 v[100:103], v[174:177], v[200:203], 0
	v_mfma_f32_16x16x32_bf16 v[96:99], v[182:185], v[200:203], 0
	v_mfma_f32_16x16x32_bf16 v[84:87], v[174:177], v[208:211], 0
	s_add_i32 m0, s33, 0x12000
	v_mfma_f32_16x16x32_bf16 v[80:83], v[182:185], v[208:211], 0
	global_load_lds_dwordx4 v144, s[76:77]
	v_mfma_f32_16x16x32_bf16 v[68:71], v[174:177], v[216:219], 0
	v_mfma_f32_16x16x32_bf16 v[64:67], v[182:185], v[216:219], 0
	v_mfma_f32_16x16x32_bf16 v[116:119], v[178:181], v[196:199], v[116:119]
	v_mfma_f32_16x16x32_bf16 v[112:115], v[188:191], v[196:199], v[112:115]
	v_mfma_f32_16x16x32_bf16 v[100:103], v[178:181], v[204:207], v[100:103]
	v_mfma_f32_16x16x32_bf16 v[96:99], v[188:191], v[204:207], v[96:99]
	v_mfma_f32_16x16x32_bf16 v[84:87], v[178:181], v[212:215], v[84:87]
	v_mfma_f32_16x16x32_bf16 v[80:83], v[188:191], v[212:215], v[80:83]
	v_mfma_f32_16x16x32_bf16 v[68:71], v[178:181], v[220:223], v[68:71]
	v_mfma_f32_16x16x32_bf16 v[64:67], v[188:191], v[220:223], v[64:67]
	s_cmp_lg_u32 s37, 1
	s_cbranch_scc1 .Lp1_kloop_rp
	s_waitcnt vmcnt(8) lgkmcnt(0)
	s_branch .Lp1_kloop_dp

; #define LAS __attribute__((address_space(3)))
; #define PG8_WAIT_V(n) asm volatile("s_waitcnt vmcnt(" #n ")" ::: "memory")
; #define PG8_BAR __builtin_amdgcn_s_barrier()
; template <class Epi, class Sched, int NSEG, bool ALIGN_EPI = true, bool AFTER_DRAIN = false>
; __device__ __forceinline__ void gemm_phase(LAS unsigned char* lds, const Gemm g, const Sched& S, const Epi& E) {
;     ...
;     PG8_WAIT_V(0);
;     if constexpr (!ALIGN_EPI) { if (wr == 0) PG8_BAR; }
;     PG8_BAR;
; __global__ void __launch_bounds__(NTHREADS, 2) fox_fwd(Args args) {
;     ...
;         for (int srep = 0; srep < SIDE_REPS; ++srep) for (int c = bx; c < 256; c += G) p1_side_task(c, (LAS unsigned char*)lds, XN, WIN, b_f, LF, Kb, Vb, P1b);
.LBB0_412:
	s_setprio 0
	s_waitcnt vmcnt(8)
	s_barrier
	s_cmpk_gt_i32 s97, 0xff
	s_cbranch_scc1 .LBB0_432
